# stack5 + relu^2 epilogue without the separate canonicalising v_max
# speedup vs baseline: 1.0065x; 1.0065x over previous
.LBB0_337:
	ds_read_b128 v[160:163], v147
	v_lshl_add_u32 v148, s62, 8, v142
	v_ashrrev_i32_e32 v149, 31, v148
	v_mul_lo_u32 v149, s68, v149
	v_mul_lo_u32 v159, s69, v148
	s_waitcnt lgkmcnt(0)
	v_mov_b32_e32 v166, v161
	v_mov_b32_e32 v167, v162
	v_mov_b32_e32 v161, v163
	v_mad_u64_u32 v[164:165], s[16:17], s68, v148, 0
	v_pk_add_f32 v[160:161], v[166:167], v[160:161]
	v_add3_u32 v165, v165, v149, v159
	v_add_f32_e32 v159, v160, v161
	v_fmamk_f32 v159, v159, 0x3a800000, v155
	v_rsq_f32_e32 v159, v159
	v_lshl_add_u64 v[160:161], v[164:165], 1, s[78:79]
	v_lshl_or_b32 v140, s63, 8, v144
	v_ashrrev_i32_e32 v141, 31, v140
	v_mul_f32_e32 v162, v159, v159
	v_max_f32_e32 v165, 0, v129
	v_max_f32_e32 v164, 0, v128
	v_max_f32_e32 v167, 0, v127
	v_max_f32_e32 v166, 0, v126
	v_pk_mul_f32 v[128:129], v[128:129], v[164:165]
	v_max_f32_e32 v165, 0, v125
	v_max_f32_e32 v164, 0, v124
	v_pk_mul_f32 v[126:127], v[126:127], v[166:167]
	v_max_f32_e32 v167, 0, v123
	v_max_f32_e32 v166, 0, v122
	v_pk_mul_f32 v[122:123], v[122:123], v[166:167]
	v_pk_mul_f32 v[124:125], v[124:125], v[164:165]
	v_lshlrev_b64 v[140:141], 1, v[140:141]
	v_pk_mul_f32 v[164:165], v[124:125], v[162:163] op_sel_hi:[1,0]
	v_pk_mul_f32 v[124:125], v[122:123], v[162:163] op_sel_hi:[1,0]
	v_lshl_add_u64 v[160:161], v[160:161], 0, v[140:141]
	v_pk_mul_f32 v[128:129], v[128:129], v[162:163] op_sel_hi:[1,0]
	v_pk_mul_f32 v[126:127], v[126:127], v[162:163] op_sel_hi:[1,0]
	s_and_b64 vcc, exec, s[6:7]
	v_cvt_pk_bf16_f32 v122, v126, v127
	v_cvt_pk_bf16_f32 v123, v128, v129
	v_cvt_pk_bf16_f32 v124, v124, v125
	v_cvt_pk_bf16_f32 v125, v164, v165
	global_store_dwordx4 v[160:161], v[122:125], off
	s_mov_b64 s[6:7], -1
	s_nop 0
	v_max_f32_e32 v123, 0, v121
	v_max_f32_e32 v125, 0, v119
	v_max_f32_e32 v122, 0, v120
	v_max_f32_e32 v124, 0, v118
	v_pk_mul_f32 v[118:119], v[118:119], v[124:125]
	v_pk_mul_f32 v[120:121], v[120:121], v[122:123]
	v_max_f32_e32 v123, 0, v117
	v_max_f32_e32 v125, 0, v115
	v_max_f32_e32 v122, 0, v116
	v_max_f32_e32 v124, 0, v114
	v_pk_mul_f32 v[114:115], v[114:115], v[124:125]
	v_pk_mul_f32 v[116:117], v[116:117], v[122:123]
	v_pk_mul_f32 v[120:121], v[120:121], v[162:163] op_sel_hi:[1,0]
	v_pk_mul_f32 v[122:123], v[116:117], v[162:163] op_sel_hi:[1,0]
	v_pk_mul_f32 v[116:117], v[114:115], v[162:163] op_sel_hi:[1,0]
	v_pk_mul_f32 v[118:119], v[118:119], v[162:163] op_sel_hi:[1,0]
	s_nop 0
	v_cvt_pk_bf16_f32 v114, v118, v119
	v_cvt_pk_bf16_f32 v115, v120, v121
	v_cvt_pk_bf16_f32 v116, v116, v117
	v_cvt_pk_bf16_f32 v117, v122, v123
	global_store_dwordx4 v[160:161], v[114:117], off offset:256
	ds_read_b128 v[114:117], v147 offset:256
	v_or_b32_e32 v118, 16, v148
	v_mul_lo_u32 v122, s69, v118
	v_mad_u64_u32 v[118:119], s[16:17], s68, v118, 0
	s_waitcnt lgkmcnt(0)
	v_mov_b32_e32 v120, v115
	v_mov_b32_e32 v121, v116
	v_mov_b32_e32 v115, v117
	v_pk_add_f32 v[114:115], v[120:121], v[114:115]
	v_add3_u32 v119, v119, v149, v122
	v_add_f32_e32 v114, v114, v115
	v_fmamk_f32 v114, v114, 0x3a800000, v155
	v_rsq_f32_e32 v116, v114
	v_lshl_add_u64 v[114:115], v[118:119], 1, s[78:79]
	v_max_f32_e32 v119, 0, v113
	v_max_f32_e32 v118, 0, v112
	v_max_f32_e32 v121, 0, v111
	v_max_f32_e32 v120, 0, v110
	v_mul_f32_e32 v116, v116, v116
	v_pk_mul_f32 v[110:111], v[110:111], v[120:121]
	v_pk_mul_f32 v[112:113], v[112:113], v[118:119]
	v_pk_mul_f32 v[110:111], v[110:111], v[116:117] op_sel_hi:[1,0]
	v_pk_mul_f32 v[112:113], v[112:113], v[116:117] op_sel_hi:[1,0]
	v_max_f32_e32 v119, 0, v109
	v_max_f32_e32 v118, 0, v108
	v_max_f32_e32 v121, 0, v107
	v_max_f32_e32 v120, 0, v106
	v_pk_mul_f32 v[106:107], v[106:107], v[120:121]
	v_pk_mul_f32 v[108:109], v[108:109], v[118:119]
	v_lshl_add_u64 v[114:115], v[114:115], 0, v[140:141]
	v_pk_mul_f32 v[118:119], v[108:109], v[116:117] op_sel_hi:[1,0]
	v_pk_mul_f32 v[108:109], v[106:107], v[116:117] op_sel_hi:[1,0]
	v_cvt_pk_bf16_f32 v106, v110, v111
	v_cvt_pk_bf16_f32 v107, v112, v113
	s_nop 0
	v_cvt_pk_bf16_f32 v108, v108, v109
	v_cvt_pk_bf16_f32 v109, v118, v119
	global_store_dwordx4 v[114:115], v[106:109], off
	s_nop 1
	v_max_f32_e32 v107, 0, v105
	v_max_f32_e32 v109, 0, v103
	v_max_f32_e32 v106, 0, v104
	v_max_f32_e32 v108, 0, v102
	v_pk_mul_f32 v[102:103], v[102:103], v[108:109]
	v_pk_mul_f32 v[104:105], v[104:105], v[106:107]
	v_max_f32_e32 v107, 0, v101
	v_max_f32_e32 v109, 0, v99
	v_max_f32_e32 v106, 0, v100
	v_max_f32_e32 v108, 0, v98
	v_pk_mul_f32 v[98:99], v[98:99], v[108:109]
	v_pk_mul_f32 v[100:101], v[100:101], v[106:107]
	v_pk_mul_f32 v[104:105], v[104:105], v[116:117] op_sel_hi:[1,0]
	v_pk_mul_f32 v[106:107], v[100:101], v[116:117] op_sel_hi:[1,0]
	v_pk_mul_f32 v[100:101], v[98:99], v[116:117] op_sel_hi:[1,0]
	v_pk_mul_f32 v[102:103], v[102:103], v[116:117] op_sel_hi:[1,0]
	s_nop 0
	v_cvt_pk_bf16_f32 v98, v102, v103
	v_cvt_pk_bf16_f32 v99, v104, v105
	v_cvt_pk_bf16_f32 v100, v100, v101
	v_cvt_pk_bf16_f32 v101, v106, v107
	global_store_dwordx4 v[114:115], v[98:101], off offset:256
	ds_read_b128 v[98:101], v147 offset:512
	v_or_b32_e32 v102, 32, v148
	v_mul_lo_u32 v106, s69, v102
	v_mad_u64_u32 v[102:103], s[16:17], s68, v102, 0
	s_waitcnt lgkmcnt(0)
	v_mov_b32_e32 v104, v99
	v_mov_b32_e32 v105, v100
	v_mov_b32_e32 v99, v101
	v_pk_add_f32 v[98:99], v[104:105], v[98:99]
	v_add3_u32 v103, v103, v149, v106
	v_add_f32_e32 v98, v98, v99
	v_fmamk_f32 v98, v98, 0x3a800000, v155
	v_rsq_f32_e32 v100, v98
	v_lshl_add_u64 v[98:99], v[102:103], 1, s[78:79]
	v_max_f32_e32 v103, 0, v97
	v_max_f32_e32 v102, 0, v96
	v_max_f32_e32 v105, 0, v95
	v_max_f32_e32 v104, 0, v94
	v_mul_f32_e32 v100, v100, v100
	v_pk_mul_f32 v[94:95], v[94:95], v[104:105]
	v_pk_mul_f32 v[96:97], v[96:97], v[102:103]
	v_pk_mul_f32 v[94:95], v[94:95], v[100:101] op_sel_hi:[1,0]
	v_pk_mul_f32 v[96:97], v[96:97], v[100:101] op_sel_hi:[1,0]
	v_max_f32_e32 v103, 0, v93
	v_max_f32_e32 v102, 0, v92
	v_max_f32_e32 v105, 0, v91
	v_max_f32_e32 v104, 0, v90
	v_pk_mul_f32 v[90:91], v[90:91], v[104:105]
	v_pk_mul_f32 v[92:93], v[92:93], v[102:103]
	v_lshl_add_u64 v[98:99], v[98:99], 0, v[140:141]
	v_pk_mul_f32 v[102:103], v[92:93], v[100:101] op_sel_hi:[1,0]
	v_pk_mul_f32 v[92:93], v[90:91], v[100:101] op_sel_hi:[1,0]
	v_cvt_pk_bf16_f32 v90, v94, v95
	v_cvt_pk_bf16_f32 v91, v96, v97
	s_nop 0
	v_cvt_pk_bf16_f32 v92, v92, v93
	v_cvt_pk_bf16_f32 v93, v102, v103
	global_store_dwordx4 v[98:99], v[90:93], off
	s_nop 1
	v_max_f32_e32 v91, 0, v89
	v_max_f32_e32 v93, 0, v87
	v_max_f32_e32 v90, 0, v88
	v_max_f32_e32 v92, 0, v86
	v_pk_mul_f32 v[86:87], v[86:87], v[92:93]
	v_pk_mul_f32 v[88:89], v[88:89], v[90:91]
	v_max_f32_e32 v91, 0, v85
	v_max_f32_e32 v93, 0, v83
	v_max_f32_e32 v90, 0, v84
	v_max_f32_e32 v92, 0, v82
	v_pk_mul_f32 v[82:83], v[82:83], v[92:93]
	v_pk_mul_f32 v[84:85], v[84:85], v[90:91]
	v_pk_mul_f32 v[88:89], v[88:89], v[100:101] op_sel_hi:[1,0]
	v_pk_mul_f32 v[90:91], v[84:85], v[100:101] op_sel_hi:[1,0]
	v_pk_mul_f32 v[84:85], v[82:83], v[100:101] op_sel_hi:[1,0]
	v_pk_mul_f32 v[86:87], v[86:87], v[100:101] op_sel_hi:[1,0]
	s_nop 0
	v_cvt_pk_bf16_f32 v82, v86, v87
	v_cvt_pk_bf16_f32 v83, v88, v89
	v_cvt_pk_bf16_f32 v84, v84, v85
	v_cvt_pk_bf16_f32 v85, v90, v91
	global_store_dwordx4 v[98:99], v[82:85], off offset:256
	ds_read_b128 v[82:85], v147 offset:768
	v_or_b32_e32 v86, 48, v148
	v_mul_lo_u32 v90, s69, v86
	v_mad_u64_u32 v[86:87], s[16:17], s68, v86, 0
	s_waitcnt lgkmcnt(0)
	v_mov_b32_e32 v88, v83
	v_mov_b32_e32 v89, v84
	v_mov_b32_e32 v83, v85
	v_pk_add_f32 v[82:83], v[88:89], v[82:83]
	v_add3_u32 v87, v87, v149, v90
	v_add_f32_e32 v82, v82, v83
	v_fmamk_f32 v82, v82, 0x3a800000, v155
	v_rsq_f32_e32 v84, v82
	v_lshl_add_u64 v[82:83], v[86:87], 1, s[78:79]
	v_max_f32_e32 v87, 0, v81
	v_max_f32_e32 v86, 0, v80
	v_max_f32_e32 v89, 0, v79
	v_max_f32_e32 v88, 0, v78
	v_mul_f32_e32 v84, v84, v84
	v_pk_mul_f32 v[78:79], v[78:79], v[88:89]
	v_pk_mul_f32 v[80:81], v[80:81], v[86:87]
	v_pk_mul_f32 v[78:79], v[78:79], v[84:85] op_sel_hi:[1,0]
	v_pk_mul_f32 v[80:81], v[80:81], v[84:85] op_sel_hi:[1,0]
	v_max_f32_e32 v87, 0, v77
	v_max_f32_e32 v86, 0, v76
	v_max_f32_e32 v89, 0, v75
	v_max_f32_e32 v88, 0, v74
	v_pk_mul_f32 v[74:75], v[74:75], v[88:89]
	v_pk_mul_f32 v[76:77], v[76:77], v[86:87]
	v_lshl_add_u64 v[82:83], v[82:83], 0, v[140:141]
	v_pk_mul_f32 v[86:87], v[76:77], v[84:85] op_sel_hi:[1,0]
	v_pk_mul_f32 v[76:77], v[74:75], v[84:85] op_sel_hi:[1,0]
	v_cvt_pk_bf16_f32 v74, v78, v79
	v_cvt_pk_bf16_f32 v75, v80, v81
	s_nop 0
	v_cvt_pk_bf16_f32 v76, v76, v77
	v_cvt_pk_bf16_f32 v77, v86, v87
	global_store_dwordx4 v[82:83], v[74:77], off
	s_nop 1
	v_max_f32_e32 v75, 0, v73
	v_max_f32_e32 v77, 0, v71
	v_max_f32_e32 v74, 0, v72
	v_max_f32_e32 v76, 0, v70
	v_pk_mul_f32 v[70:71], v[70:71], v[76:77]
	v_pk_mul_f32 v[72:73], v[72:73], v[74:75]
	v_max_f32_e32 v75, 0, v69
	v_max_f32_e32 v77, 0, v67
	v_max_f32_e32 v74, 0, v68
	v_max_f32_e32 v76, 0, v66
	v_pk_mul_f32 v[66:67], v[66:67], v[76:77]
	v_pk_mul_f32 v[68:69], v[68:69], v[74:75]
	v_pk_mul_f32 v[72:73], v[72:73], v[84:85] op_sel_hi:[1,0]
	v_pk_mul_f32 v[74:75], v[68:69], v[84:85] op_sel_hi:[1,0]
	v_pk_mul_f32 v[68:69], v[66:67], v[84:85] op_sel_hi:[1,0]
	v_pk_mul_f32 v[70:71], v[70:71], v[84:85] op_sel_hi:[1,0]
	s_nop 0
	v_cvt_pk_bf16_f32 v66, v70, v71
	v_cvt_pk_bf16_f32 v67, v72, v73
	v_cvt_pk_bf16_f32 v68, v68, v69
	v_cvt_pk_bf16_f32 v69, v74, v75
	global_store_dwordx4 v[82:83], v[66:69], off offset:256
	ds_read_b128 v[66:69], v147 offset:1024
	v_add_u32_e32 v70, 0x80, v148
	v_ashrrev_i32_e32 v71, 31, v70
	v_mul_lo_u32 v74, s68, v71
	v_mul_lo_u32 v75, s69, v70
	s_waitcnt lgkmcnt(0)
	v_mov_b32_e32 v72, v67
	v_mov_b32_e32 v73, v68
	v_mov_b32_e32 v67, v69
	v_pk_add_f32 v[66:67], v[72:73], v[66:67]
	v_mad_u64_u32 v[70:71], s[16:17], s68, v70, 0
	v_add_f32_e32 v66, v66, v67
	v_fmamk_f32 v66, v66, 0x3a800000, v155
	v_add3_u32 v71, v71, v74, v75
	v_rsq_f32_e32 v68, v66
	v_lshl_add_u64 v[66:67], v[70:71], 1, s[78:79]
	v_max_f32_e32 v71, 0, v65
	v_max_f32_e32 v70, 0, v64
	v_max_f32_e32 v73, 0, v63
	v_max_f32_e32 v72, 0, v62
	v_mul_f32_e32 v68, v68, v68
	v_pk_mul_f32 v[62:63], v[62:63], v[72:73]
	v_pk_mul_f32 v[64:65], v[64:65], v[70:71]
	v_pk_mul_f32 v[62:63], v[62:63], v[68:69] op_sel_hi:[1,0]
	v_pk_mul_f32 v[64:65], v[64:65], v[68:69] op_sel_hi:[1,0]
	v_max_f32_e32 v71, 0, v61
	v_max_f32_e32 v70, 0, v60
	v_max_f32_e32 v73, 0, v59
	v_max_f32_e32 v72, 0, v58
	v_pk_mul_f32 v[58:59], v[58:59], v[72:73]
	v_pk_mul_f32 v[60:61], v[60:61], v[70:71]
	v_lshl_add_u64 v[66:67], v[66:67], 0, v[140:141]
	v_pk_mul_f32 v[70:71], v[60:61], v[68:69] op_sel_hi:[1,0]
	v_pk_mul_f32 v[60:61], v[58:59], v[68:69] op_sel_hi:[1,0]
	v_cvt_pk_bf16_f32 v58, v62, v63
	v_cvt_pk_bf16_f32 v59, v64, v65
	s_nop 0
	v_cvt_pk_bf16_f32 v60, v60, v61
	v_cvt_pk_bf16_f32 v61, v70, v71
	global_store_dwordx4 v[66:67], v[58:61], off
	s_nop 1
	v_max_f32_e32 v59, 0, v57
	v_max_f32_e32 v61, 0, v55
	v_max_f32_e32 v58, 0, v56
	v_max_f32_e32 v60, 0, v54
	v_pk_mul_f32 v[54:55], v[54:55], v[60:61]
	v_pk_mul_f32 v[56:57], v[56:57], v[58:59]
	v_max_f32_e32 v59, 0, v53
	v_max_f32_e32 v61, 0, v51
	v_max_f32_e32 v58, 0, v52
	v_max_f32_e32 v60, 0, v50
	v_pk_mul_f32 v[50:51], v[50:51], v[60:61]
	v_pk_mul_f32 v[52:53], v[52:53], v[58:59]
	v_pk_mul_f32 v[56:57], v[56:57], v[68:69] op_sel_hi:[1,0]
	v_pk_mul_f32 v[58:59], v[52:53], v[68:69] op_sel_hi:[1,0]
	v_pk_mul_f32 v[52:53], v[50:51], v[68:69] op_sel_hi:[1,0]
	v_pk_mul_f32 v[54:55], v[54:55], v[68:69] op_sel_hi:[1,0]
	s_nop 0
	v_cvt_pk_bf16_f32 v50, v54, v55
	v_cvt_pk_bf16_f32 v51, v56, v57
	v_cvt_pk_bf16_f32 v52, v52, v53
	v_cvt_pk_bf16_f32 v53, v58, v59
	global_store_dwordx4 v[66:67], v[50:53], off offset:256
	ds_read_b128 v[50:53], v147 offset:1280
	v_add_u32_e32 v54, 0x90, v148
	v_ashrrev_i32_e32 v55, 31, v54
	v_mul_lo_u32 v58, s68, v55
	v_mul_lo_u32 v59, s69, v54
	s_waitcnt lgkmcnt(0)
	v_mov_b32_e32 v56, v51
	v_mov_b32_e32 v57, v52
	v_mov_b32_e32 v51, v53
	v_pk_add_f32 v[50:51], v[56:57], v[50:51]
	v_mad_u64_u32 v[54:55], s[16:17], s68, v54, 0
	v_add_f32_e32 v50, v50, v51
	v_fmamk_f32 v50, v50, 0x3a800000, v155
	v_add3_u32 v55, v55, v58, v59
	v_rsq_f32_e32 v52, v50
	v_lshl_add_u64 v[50:51], v[54:55], 1, s[78:79]
	v_max_f32_e32 v55, 0, v49
	v_max_f32_e32 v54, 0, v48
	v_max_f32_e32 v57, 0, v47
	v_max_f32_e32 v56, 0, v46
	v_mul_f32_e32 v52, v52, v52
	v_pk_mul_f32 v[46:47], v[46:47], v[56:57]
	v_pk_mul_f32 v[48:49], v[48:49], v[54:55]
	v_pk_mul_f32 v[46:47], v[46:47], v[52:53] op_sel_hi:[1,0]
	v_pk_mul_f32 v[48:49], v[48:49], v[52:53] op_sel_hi:[1,0]
	v_max_f32_e32 v55, 0, v45
	v_max_f32_e32 v54, 0, v44
	v_max_f32_e32 v57, 0, v43
	v_max_f32_e32 v56, 0, v42
	v_pk_mul_f32 v[42:43], v[42:43], v[56:57]
	v_pk_mul_f32 v[44:45], v[44:45], v[54:55]
	v_lshl_add_u64 v[50:51], v[50:51], 0, v[140:141]
	v_pk_mul_f32 v[54:55], v[44:45], v[52:53] op_sel_hi:[1,0]
	v_pk_mul_f32 v[44:45], v[42:43], v[52:53] op_sel_hi:[1,0]
	v_cvt_pk_bf16_f32 v42, v46, v47
	v_cvt_pk_bf16_f32 v43, v48, v49
	s_nop 0
	v_cvt_pk_bf16_f32 v44, v44, v45
	v_cvt_pk_bf16_f32 v45, v54, v55
	global_store_dwordx4 v[50:51], v[42:45], off
	s_nop 1
	v_max_f32_e32 v43, 0, v41
	v_max_f32_e32 v45, 0, v39
	v_max_f32_e32 v42, 0, v40
	v_max_f32_e32 v44, 0, v38
	v_pk_mul_f32 v[38:39], v[38:39], v[44:45]
	v_pk_mul_f32 v[40:41], v[40:41], v[42:43]
	v_max_f32_e32 v43, 0, v37
	v_max_f32_e32 v45, 0, v35
	v_max_f32_e32 v42, 0, v36
	v_max_f32_e32 v44, 0, v34
	v_pk_mul_f32 v[34:35], v[34:35], v[44:45]
	v_pk_mul_f32 v[36:37], v[36:37], v[42:43]
	v_pk_mul_f32 v[40:41], v[40:41], v[52:53] op_sel_hi:[1,0]
	v_pk_mul_f32 v[42:43], v[36:37], v[52:53] op_sel_hi:[1,0]
	v_pk_mul_f32 v[36:37], v[34:35], v[52:53] op_sel_hi:[1,0]
	v_pk_mul_f32 v[38:39], v[38:39], v[52:53] op_sel_hi:[1,0]
	s_nop 0
	v_cvt_pk_bf16_f32 v34, v38, v39
	v_cvt_pk_bf16_f32 v35, v40, v41
	v_cvt_pk_bf16_f32 v36, v36, v37
	v_cvt_pk_bf16_f32 v37, v42, v43
	global_store_dwordx4 v[50:51], v[34:37], off offset:256
	ds_read_b128 v[34:37], v147 offset:1536
	v_add_u32_e32 v38, 0xa0, v148
	v_ashrrev_i32_e32 v39, 31, v38
	v_mul_lo_u32 v42, s68, v39
	v_mul_lo_u32 v43, s69, v38
	s_waitcnt lgkmcnt(0)
	v_mov_b32_e32 v40, v35
	v_mov_b32_e32 v41, v36
	v_mov_b32_e32 v35, v37
	v_pk_add_f32 v[34:35], v[40:41], v[34:35]
	v_mad_u64_u32 v[38:39], s[16:17], s68, v38, 0
	v_add_f32_e32 v34, v34, v35
	v_fmamk_f32 v34, v34, 0x3a800000, v155
	v_add3_u32 v39, v39, v42, v43
	v_rsq_f32_e32 v36, v34
	v_lshl_add_u64 v[34:35], v[38:39], 1, s[78:79]
	v_max_f32_e32 v39, 0, v33
	v_max_f32_e32 v38, 0, v32
	v_max_f32_e32 v41, 0, v31
	v_max_f32_e32 v40, 0, v30
	v_mul_f32_e32 v36, v36, v36
	v_pk_mul_f32 v[30:31], v[30:31], v[40:41]
	v_pk_mul_f32 v[32:33], v[32:33], v[38:39]
	v_pk_mul_f32 v[30:31], v[30:31], v[36:37] op_sel_hi:[1,0]
	v_pk_mul_f32 v[32:33], v[32:33], v[36:37] op_sel_hi:[1,0]
	v_max_f32_e32 v39, 0, v29
	v_max_f32_e32 v38, 0, v28
	v_max_f32_e32 v41, 0, v27
	v_max_f32_e32 v40, 0, v26
	v_pk_mul_f32 v[26:27], v[26:27], v[40:41]
	v_pk_mul_f32 v[28:29], v[28:29], v[38:39]
	v_lshl_add_u64 v[34:35], v[34:35], 0, v[140:141]
	v_pk_mul_f32 v[38:39], v[28:29], v[36:37] op_sel_hi:[1,0]
	v_pk_mul_f32 v[28:29], v[26:27], v[36:37] op_sel_hi:[1,0]
	v_cvt_pk_bf16_f32 v26, v30, v31
	v_cvt_pk_bf16_f32 v27, v32, v33
	s_nop 0
	v_cvt_pk_bf16_f32 v28, v28, v29
	v_cvt_pk_bf16_f32 v29, v38, v39
	global_store_dwordx4 v[34:35], v[26:29], off
	s_nop 1
	v_max_f32_e32 v27, 0, v25
	v_max_f32_e32 v29, 0, v23
	v_max_f32_e32 v26, 0, v24
	v_max_f32_e32 v28, 0, v22
	v_pk_mul_f32 v[22:23], v[22:23], v[28:29]
	v_pk_mul_f32 v[24:25], v[24:25], v[26:27]
	v_max_f32_e32 v27, 0, v21
	v_max_f32_e32 v29, 0, v19
	v_max_f32_e32 v26, 0, v20
	v_max_f32_e32 v28, 0, v18
	v_pk_mul_f32 v[18:19], v[18:19], v[28:29]
	v_pk_mul_f32 v[20:21], v[20:21], v[26:27]
	v_pk_mul_f32 v[24:25], v[24:25], v[36:37] op_sel_hi:[1,0]
	v_pk_mul_f32 v[26:27], v[20:21], v[36:37] op_sel_hi:[1,0]
	v_pk_mul_f32 v[20:21], v[18:19], v[36:37] op_sel_hi:[1,0]
	v_pk_mul_f32 v[22:23], v[22:23], v[36:37] op_sel_hi:[1,0]
	s_nop 0
	v_cvt_pk_bf16_f32 v18, v22, v23
	v_cvt_pk_bf16_f32 v19, v24, v25
	v_cvt_pk_bf16_f32 v20, v20, v21
	v_cvt_pk_bf16_f32 v21, v26, v27
	global_store_dwordx4 v[34:35], v[18:21], off offset:256
	ds_read_b128 v[18:21], v147 offset:1792
	v_add_u32_e32 v22, 0xb0, v148
	v_ashrrev_i32_e32 v23, 31, v22
	v_mul_lo_u32 v26, s68, v23
	v_mul_lo_u32 v27, s69, v22
	s_waitcnt lgkmcnt(0)
	v_mov_b32_e32 v24, v19
	v_mov_b32_e32 v25, v20
	v_mov_b32_e32 v19, v21
	v_pk_add_f32 v[18:19], v[24:25], v[18:19]
	v_mad_u64_u32 v[22:23], s[16:17], s68, v22, 0
	v_add_f32_e32 v18, v18, v19
	v_fmamk_f32 v18, v18, 0x3a800000, v155
	v_add3_u32 v23, v23, v26, v27
	v_rsq_f32_e32 v20, v18
	v_lshl_add_u64 v[18:19], v[22:23], 1, s[78:79]
	v_max_f32_e32 v23, 0, v17
	v_max_f32_e32 v22, 0, v16
	v_max_f32_e32 v25, 0, v15
	v_max_f32_e32 v24, 0, v14
	v_mul_f32_e32 v20, v20, v20
	v_pk_mul_f32 v[14:15], v[14:15], v[24:25]
	v_pk_mul_f32 v[16:17], v[16:17], v[22:23]
	v_pk_mul_f32 v[14:15], v[14:15], v[20:21] op_sel_hi:[1,0]
	v_pk_mul_f32 v[16:17], v[16:17], v[20:21] op_sel_hi:[1,0]
	v_max_f32_e32 v23, 0, v13
	v_max_f32_e32 v22, 0, v12
	v_max_f32_e32 v25, 0, v11
	v_max_f32_e32 v24, 0, v10
	v_pk_mul_f32 v[10:11], v[10:11], v[24:25]
	v_pk_mul_f32 v[12:13], v[12:13], v[22:23]
	v_lshl_add_u64 v[18:19], v[18:19], 0, v[140:141]
	v_pk_mul_f32 v[22:23], v[12:13], v[20:21] op_sel_hi:[1,0]
	v_pk_mul_f32 v[12:13], v[10:11], v[20:21] op_sel_hi:[1,0]
	v_cvt_pk_bf16_f32 v10, v14, v15
	v_cvt_pk_bf16_f32 v11, v16, v17
	s_nop 0
	v_cvt_pk_bf16_f32 v12, v12, v13
	v_cvt_pk_bf16_f32 v13, v22, v23
	global_store_dwordx4 v[18:19], v[10:13], off
	s_nop 1
	v_max_f32_e32 v11, 0, v9
	v_max_f32_e32 v13, 0, v7
	v_max_f32_e32 v10, 0, v8
	v_max_f32_e32 v12, 0, v6
	v_pk_mul_f32 v[6:7], v[6:7], v[12:13]
	v_pk_mul_f32 v[8:9], v[8:9], v[10:11]
	v_max_f32_e32 v11, 0, v5
	v_max_f32_e32 v13, 0, v3
	v_max_f32_e32 v10, 0, v4
	v_max_f32_e32 v12, 0, v2
	v_pk_mul_f32 v[2:3], v[2:3], v[12:13]
	v_pk_mul_f32 v[4:5], v[4:5], v[10:11]
	v_pk_mul_f32 v[8:9], v[8:9], v[20:21] op_sel_hi:[1,0]
	v_pk_mul_f32 v[10:11], v[4:5], v[20:21] op_sel_hi:[1,0]
	v_pk_mul_f32 v[4:5], v[2:3], v[20:21] op_sel_hi:[1,0]
	v_pk_mul_f32 v[6:7], v[6:7], v[20:21] op_sel_hi:[1,0]
	s_nop 0
	v_cvt_pk_bf16_f32 v2, v6, v7
	v_cvt_pk_bf16_f32 v3, v8, v9
	v_cvt_pk_bf16_f32 v4, v4, v5
	v_cvt_pk_bf16_f32 v5, v10, v11
	global_store_dwordx4 v[18:19], v[2:5], off offset:256
	s_cbranch_vccnz .LBB0_325
	s_nop 0
	v_lshl_add_u32 v2, s61, 8, v145
	v_ashrrev_i32_e32 v3, 31, v2
	s_mov_b32 m0, s18
	v_lshl_add_u64 v[2:3], v[2:3], 4, s[96:97]
	s_mov_b64 s[6:7], 0x800
	global_load_lds_dwordx4 v[2:3], off
	v_lshl_add_u64 v[2:3], v[2:3], 0, s[6:7]
	s_add_i32 m0, s18, 0x400
	s_andn2_b64 vcc, exec, s[8:9]
	global_load_lds_dwordx4 v[2:3], off
	s_cbranch_vccnz .LBB0_324
	s_barrier
	s_branch .LBB0_324
